# opt2 plus a 1us-per-XCD-group start stagger of the multi-unit GEMM phases
# baseline (speedup 1.0000x reference)
;     __host__ __device__ bool next(int i, Unit& u) const {
;         const long L = (long)i * G + c; if (L >= nwg) return false;
;         int wgid = (int)L; { const int q = nwg / NXCD, r = nwg % NXCD, xcd = wgid % NXCD, off = wgid / NXCD; wgid = (xcd < r ? xcd * (q + 1) : r * (q + 1) + (xcd - r) * q) + off; }
; template <class Epi, class Sched, bool ALIGN_EPI = false, bool SP2 = false>
; __device__ __forceinline__ void gemm_phase(PG8_LAS unsigned char* lds, const Gemm g, const Sched& S, const Epi& E) {
;     ...
;     if (!S.next(0, cur)) return;
.LBB0_39:
	s_andn2_b64 vcc, exec, s[14:15]
	v_writelane_b32 v253, s27, 27
	s_cbranch_vccnz .LBB0_80
	s_lshl_b32 s90, s20, 5
	s_cmp_lt_i32 s68, s90
	v_readfirstlane_b32 s23, v210
	s_cbranch_scc0 .LBB0_80
	s_cmp_lt_u32 s20, 9
	s_cbranch_scc1 .Lstg_skip
	s_and_b32 s28, s68, 7
	s_mul_i32 s28, s28, 100
	s_lshr_b32 s29, s68, 3
	s_mul_i32 s29, s29, 0
	s_add_u32 s28, s28, s29
	s_memrealtime s[24:25]
	s_waitcnt lgkmcnt(0)
